# attention pair loop: O accumulators stay in one register bank for the whole iteration (2x16 v_mov_b64 copies and their MFMA drain removed), both layers
# speedup vs baseline: 1.0301x; 1.0004x over previous
; #define LAS __attribute__((address_space(3)))
; __device__ __forceinline__ void att_qk_exp(const LAS char* kb, const bf16x8 (&qf)[6], float nm, fa::f32x16& n0, fa::f32x16& n1, fa::f32x16& p0, fa::f32x16& p1, float& lsum, bf16x8 (&pf)[4]) {
;     const fa::f32x16 zero = {0.f, 0.f, 0.f, 0.f, 0.f, 0.f, 0.f, 0.f, 0.f, 0.f, 0.f, 0.f, 0.f, 0.f, 0.f, 0.f};
;     bf16x8 kc0 = *(const LAS bf16x8*)kb, kc1 = *(const LAS bf16x8*)(kb + 32 * fa::KP_A);
;     float ps = 0.f, ps2 = 0.f;
; #pragma unroll
;     for (int st = 0; st < 6; ++st) {
;         bf16x8 kn0 = kc0, kn1 = kc1;
;         if (st < 5) { kn0 = *(const LAS bf16x8*)(kb + 32 * (st + 1)); kn1 = *(const LAS bf16x8*)(kb + 32 * fa::KP_A + 32 * (st + 1)); }
;         n0 = __builtin_amdgcn_mfma_f32_32x32x16_bf16(kc0, qf[st], st == 0 ? zero : n0, 0, 0, 0);
;         n1 = __builtin_amdgcn_mfma_f32_32x32x16_bf16(kc1, qf[st], st == 0 ? zero : n1, 0, 0, 0);
;         constexpr int lo[7] = {0, 2, 6, 8, 10, 14, 16};
; #pragma unroll
;         for (int r = lo[st]; r < lo[st + 1]; ++r) {
;             p0[r] = __builtin_amdgcn_exp2f(vadd1(p0[r], nm)); p1[r] = __builtin_amdgcn_exp2f(vadd1(p1[r], nm));
;             ps += p0[r]; ps += p1[r]; }
;         kc0 = kn0; kc1 = kn1;
;         __builtin_amdgcn_sched_barrier(0);
;     }
;     lsum += ps + ps2;
;     pf[0] = fa::pack_p(p0, 0); pf[1] = fa::pack_p(p0, 8); pf[2] = fa::pack_p(p1, 0); pf[3] = fa::pack_p(p1, 8);
; }
; __device__ __forceinline__ float att_pv_max(fa::f32x16& o0, fa::f32x16& o1, const LAS char* vb, const bf16x8 (&pf)[4], const fa::f32x16& n0, const fa::f32x16& n1) {
;     using namespace fa;
;     float ta = n0[0], tb = n1[0];
;     s16x4 a0 = vtr(vb), a1 = vtr(vb + 512), b0 = vtr(vb + 4096), b1 = vtr(vb + 4096 + 512);
; #pragma unroll
;     for (int ks = 0; ks < 4; ++ks) {
;         s16x4 na0 = a0, na1 = a1, nb0 = b0, nb1 = b1;
;         if (ks < 3) { na0 = vtr(vb + (ks + 1) * 1024); na1 = vtr(vb + (ks + 1) * 1024 + 512); nb0 = vtr(vb + 4096 + (ks + 1) * 1024); nb1 = vtr(vb + 4096 + (ks + 1) * 1024 + 512); }
;         const bf16x8 v0 = (bf16x8){a0[0], a0[1], a0[2], a0[3], a1[0], a1[1], a1[2], a1[3]}, v1 = (bf16x8){b0[0], b0[1], b0[2], b0[3], b1[0], b1[1], b1[2], b1[3]};
;         o0 = __builtin_amdgcn_mfma_f32_32x32x16_bf16(v0, pf[ks], o0, 0, 0, 0);
;         o1 = __builtin_amdgcn_mfma_f32_32x32x16_bf16(v1, pf[ks], o1, 0, 0, 0);
; #pragma unroll
.LBB0_1031:
	s_add_i32 s8, s8, 0
	v_add3_u32 v67, s8, v187, v180
	ds_read_b128 v[34:37], v67 offset:21504
	ds_read_b128 v[50:53], v67 offset:28160
	ds_read_b128 v[68:71], v67 offset:21536
	v_xor_b32_e32 v84, 0x80000000, v190
	v_add_f32 v2, v2, v84
	s_waitcnt lgkmcnt(1)
	v_mfma_f32_32x32x16_bf16 v[50:65], v[50:53], v[132:135], 0
	v_add_f32 v18, v18, v84
	ds_read_b128 v[72:75], v67 offset:28192
	v_add_f32 v3, v3, v84
	v_add_f32 v19, v19, v84
	v_exp_f32_e32 v2, v2
	v_exp_f32_e32 v18, v18
	v_exp_f32_e32 v3, v3
	v_mfma_f32_32x32x16_bf16 v[34:49], v[34:37], v[132:135], 0
	v_exp_f32_e32 v19, v19
	s_waitcnt lgkmcnt(1)
	v_mfma_f32_32x32x16_bf16 v[34:49], v[68:71], v[136:139], v[34:49]
	ds_read_b128 v[76:79], v67 offset:21568
	ds_read_b128 v[80:83], v67 offset:28224
	v_add_f32 v4, v4, v84
	v_add_f32 v20, v20, v84
	v_add_f32 v5, v5, v84
	v_add_f32 v21, v21, v84
	v_add_f32 v6, v6, v84
	v_add_f32 v22, v22, v84
	s_waitcnt lgkmcnt(2)
	v_mfma_f32_32x32x16_bf16 v[50:65], v[72:75], v[136:139], v[50:65]
	v_add_f32 v7, v7, v84
	v_add_f32 v23, v23, v84
	v_exp_f32_e32 v4, v4
	v_exp_f32_e32 v20, v20
	v_exp_f32_e32 v5, v5
	v_exp_f32_e32 v21, v21
	v_exp_f32_e32 v6, v6
	v_exp_f32_e32 v22, v22
	v_exp_f32_e32 v7, v7
	v_exp_f32_e32 v23, v23
	s_waitcnt lgkmcnt(1)
	v_mfma_f32_32x32x16_bf16 v[34:49], v[76:79], v[140:143], v[34:49]
	ds_read_b128 v[68:71], v67 offset:21600
	ds_read_b128 v[72:75], v67 offset:28256
	v_add_f32 v8, v8, v84
	v_add_f32 v24, v24, v84
	v_add_f32 v9, v9, v84
	v_add_f32 v25, v25, v84
	s_nop 0
	v_exp_f32_e32 v8, v8
	s_waitcnt lgkmcnt(2)
	v_mfma_f32_32x32x16_bf16 v[50:65], v[80:83], v[140:143], v[50:65]
	v_exp_f32_e32 v24, v24
	v_exp_f32_e32 v9, v9
	v_exp_f32_e32 v25, v25
	s_waitcnt lgkmcnt(1)
	v_mfma_f32_32x32x16_bf16 v[34:49], v[68:71], v[144:147], v[34:49]
	ds_read_b128 v[76:79], v67 offset:21632
	ds_read_b128 v[80:83], v67 offset:28288
	v_add_f32 v10, v10, v84
	v_add_f32 v26, v26, v84
	v_add_f32 v11, v11, v84
	v_add_f32 v27, v27, v84
	s_nop 0
	v_exp_f32_e32 v10, v10
	s_waitcnt lgkmcnt(2)
	v_mfma_f32_32x32x16_bf16 v[50:65], v[72:75], v[144:147], v[50:65]
	v_exp_f32_e32 v26, v26
	v_exp_f32_e32 v11, v11
	v_exp_f32_e32 v27, v27
	s_waitcnt lgkmcnt(1)
	v_mfma_f32_32x32x16_bf16 v[34:49], v[76:79], v[148:151], v[34:49]
	ds_read_b128 v[68:71], v67 offset:21664
	ds_read_b128 v[72:75], v67 offset:28320
	v_add_f32 v12, v12, v84
	v_add_f32 v28, v28, v84
	v_add_f32 v13, v13, v84
	v_add_f32 v29, v29, v84
	v_add_f32 v14, v14, v84
	v_add_f32 v30, v30, v84
	s_waitcnt lgkmcnt(2)
	v_mfma_f32_32x32x16_bf16 v[50:65], v[80:83], v[148:151], v[50:65]
	v_add_f32 v15, v15, v84
	v_add_f32 v31, v31, v84
	v_exp_f32_e32 v12, v12
	v_exp_f32_e32 v28, v28
	v_exp_f32_e32 v13, v13
	v_exp_f32_e32 v29, v29
	v_exp_f32_e32 v14, v14
	v_exp_f32_e32 v30, v30
	v_exp_f32_e32 v15, v15
	v_exp_f32_e32 v31, v31
	v_add_f32_e32 v67, 0, v2
	v_add_f32_e32 v67, v18, v67
	v_add_f32_e32 v67, v67, v3
	v_add_f32_e32 v67, v19, v67
	v_add_f32_e32 v67, v67, v4
	v_add_f32_e32 v67, v20, v67
	v_add_f32_e32 v67, v67, v5
	v_add_f32_e32 v67, v21, v67
	v_add_f32_e32 v67, v67, v6
	v_add_f32_e32 v67, v22, v67
	v_add_f32_e32 v67, v67, v7
	v_add_f32_e32 v67, v23, v67
	v_add_f32_e32 v67, v67, v8
	v_add_f32_e32 v67, v24, v67
	v_add_f32_e32 v67, v67, v9
	v_add_f32_e32 v67, v25, v67
	v_add_f32_e32 v67, v67, v10
	v_add_f32_e32 v67, v26, v67
	v_add_f32_e32 v67, v67, v11
	v_add_f32_e32 v67, v27, v67
	v_add_f32_e32 v67, v67, v12
	v_add_f32_e32 v67, v28, v67
	v_add_f32_e32 v67, v67, v13
	v_add_f32 v16, v16, v84
	v_add_f32_e32 v67, v29, v67
	v_exp_f32_e32 v16, v16
	v_add_f32 v32, v32, v84
	s_waitcnt lgkmcnt(1)
	v_mfma_f32_32x32x16_bf16 v[34:49], v[68:71], v[152:155], v[34:49]
	v_add_f32_e32 v67, v67, v14
	v_exp_f32_e32 v32, v32
	v_add_f32 v17, v17, v84
	v_add_f32_e32 v67, v30, v67
	v_exp_f32_e32 v17, v17
	v_add_f32 v33, v33, v84
	v_add_f32_e32 v67, v67, v15
	s_waitcnt lgkmcnt(0)
	v_mfma_f32_32x32x16_bf16 v[50:65], v[72:75], v[152:155], v[50:65]
	v_exp_f32_e32 v33, v33
	v_add_f32_e32 v67, v31, v67
	v_add_f32_e32 v67, v67, v16
	v_add_f32_e32 v67, v32, v67
	v_add_f32_e32 v67, v67, v17
	v_add_f32_e32 v67, v33, v67
	v_add_u32_e32 v193, s8, v189
	v_cvt_pk_bf16_f32 v68, v2, v3
	v_cvt_pk_bf16_f32 v69, v4, v5
	v_cvt_pk_bf16_f32 v70, v6, v7
	v_cvt_pk_bf16_f32 v71, v8, v9
	v_cvt_pk_bf16_f32 v72, v10, v11
	v_cvt_pk_bf16_f32 v73, v12, v13
	v_cvt_pk_bf16_f32 v74, v14, v15
	v_cvt_pk_bf16_f32 v75, v16, v17
	v_cvt_pk_bf16_f32 v76, v18, v19
	v_cvt_pk_bf16_f32 v77, v20, v21
	v_cvt_pk_bf16_f32 v78, v22, v23
	v_cvt_pk_bf16_f32 v79, v24, v25
	v_cvt_pk_bf16_f32 v196, v26, v27
	v_cvt_pk_bf16_f32 v197, v28, v29
	v_cvt_pk_bf16_f32 v198, v30, v31
	v_cvt_pk_bf16_f32 v199, v32, v33
	ds_read_b64_tr_b16 v[80:81], v193 offset:13312
	ds_read_b64_tr_b16 v[82:83], v193 offset:13824
	ds_read_b64_tr_b16 v[84:85], v193 offset:14336
	ds_read_b64_tr_b16 v[86:87], v193 offset:14848
	s_waitcnt lgkmcnt(2)
	v_mfma_f32_32x32x16_bf16 v[114:129], v[80:83], v[68:71], v[114:129]
	ds_read_b64_tr_b16 v[80:81], v193 offset:17408
	ds_read_b64_tr_b16 v[82:83], v193 offset:17920
	ds_read_b64_tr_b16 v[88:89], v193 offset:18432
	ds_read_b64_tr_b16 v[90:91], v193 offset:18944
	v_add_f32_e32 v67, 0, v67
	v_add_f32_e32 v192, v66, v67
	s_waitcnt lgkmcnt(2)
	v_mfma_f32_32x32x16_bf16 v[98:113], v[80:83], v[68:71], v[98:113]
	s_waitcnt lgkmcnt(0)
	v_mfma_f32_32x32x16_bf16 v[98:113], v[88:91], v[72:75], v[98:113]
	ds_read_b64_tr_b16 v[66:67], v193 offset:15360
	ds_read_b64_tr_b16 v[68:69], v193 offset:15872
	ds_read_b64_tr_b16 v[80:81], v193 offset:19456
	ds_read_b64_tr_b16 v[82:83], v193 offset:19968
	v_mfma_f32_32x32x16_bf16 v[114:129], v[84:87], v[72:75], v[114:129]
	s_waitcnt lgkmcnt(0)
	v_mfma_f32_32x32x16_bf16 v[98:113], v[80:83], v[76:79], v[98:113]
	ds_read_b64_tr_b16 v[84:85], v193 offset:16384
	ds_read_b64_tr_b16 v[86:87], v193 offset:16896
	ds_read_b64_tr_b16 v[200:201], v193 offset:20480
	ds_read_b64_tr_b16 v[202:203], v193 offset:20992
	v_mfma_f32_32x32x16_bf16 v[114:129], v[66:69], v[76:79], v[114:129]
	v_max_f32_e32 v66, v51, v51
	v_max_f32_e32 v67, v50, v50
	v_max_f32_e32 v66, v67, v66
	v_max3_f32 v66, v66, v52, v53
	v_max3_f32 v66, v66, v54, v55
	v_max3_f32 v66, v66, v56, v57
	v_max3_f32 v82, v66, v58, v59
	v_max3_f32 v66, v82, v60, v61
	v_max3_f32 v82, v34, v35, v36
	v_max3_f32 v82, v82, v37, v38
	v_max3_f32 v82, v82, v39, v40
	v_max3_f32 v82, v82, v41, v42
	s_waitcnt lgkmcnt(2)
	v_mfma_f32_32x32x16_bf16 v[114:129], v[84:87], v[196:199], v[114:129]
	v_max3_f32 v67, v82, v43, v44
	v_max3_f32 v82, v67, v45, v46
	v_max3_f32 v83, v66, v62, v63
	s_waitcnt lgkmcnt(0)
	v_mfma_f32_32x32x16_bf16 v[98:113], v[200:203], v[196:199], v[98:113]
	v_max3_f32 v82, v82, v47, v48
	v_max3_f32 v83, v83, v64, v65
	v_max3_f32 v82, v82, v49, v83
	v_cmp_gt_f32_e32 vcc, v82, v194
	s_cbranch_vccz .LBB0_1033
; __device__ __forceinline__ bf16x8 pack_p(const f32x16& p, int base) { u32x4 w; w.x = pk2(p[base], p[base + 1]); w.y = pk2(p[base + 2], p[base + 3]); w.z = pk2(p[base + 4], p[base + 5]); w.w = pk2(p[base + 6], p[base + 7]); return __builtin_bit_cast(bf16x8, w); }
; __device__ __forceinline__ float vadd1(float a, float b) { float r; asm("v_add_f32 %0, %1, %2" : "=v"(r) : "v"(a), "v"(b)); return r; }
; __device__ __forceinline__ void att_shift(float tm, bool first, float& mrun, float& lsum, fa::f32x16& o0, fa::f32x16& o1) {
;     if (first || __any(tm > mrun + 8.f)) {
;         tm = fmaxf(tm, __shfl_xor(tm, 32));
;         const float dl = first ? 0.f : fmaxf(tm - mrun, 0.f), alpha = __builtin_amdgcn_exp2f(-dl);
;         mrun = first ? tm : mrun + dl; lsum *= alpha;
; #pragma unroll
;         for (int r = 0; r < 16; ++r) { o0[r] *= alpha; o1[r] *= alpha; }
;     }
; }
; __device__ __forceinline__ void att_exp_pack(fa::f32x16& p0, fa::f32x16& p1, float nm, float& lsum, bf16x8 (&pf)[4]) {
;     float ps = 0.f, ps2 = 0.f;
; #pragma unroll
;     for (int r = 0; r < 16; ++r) { p0[r] = __builtin_amdgcn_exp2f(vadd1(p0[r], nm)); p1[r] = __builtin_amdgcn_exp2f(vadd1(p1[r], nm)); ps += p0[r]; ps += p1[r]; }
;     lsum += ps + ps2;
;     pf[0] = fa::pack_p(p0, 0); pf[1] = fa::pack_p(p0, 8); pf[2] = fa::pack_p(p1, 0); pf[3] = fa::pack_p(p1, 8);
; }
	v_and_b32_e32 v84, 64, v1
	v_xor_b32_e32 v83, 32, v1
	v_add_u32_e32 v84, 64, v84
	v_cmp_lt_i32_e32 vcc, v83, v84
	s_nop 1
	v_cndmask_b32_e32 v83, v1, v83, vcc
	v_lshlrev_b32_e32 v83, 2, v83
	ds_bpermute_b32 v83, v83, v82
	v_max_f32_e32 v82, v82, v82
	s_waitcnt lgkmcnt(0)
	v_max_f32_e32 v83, v83, v83
	v_max_f32_e32 v82, v82, v83
	v_sub_f32_e32 v82, v82, v190
	v_max_f32_e32 v83, 0, v82
	v_exp_f32_e64 v82, -v83
	v_add_f32_e32 v190, v190, v83
	v_mul_f32_e32 v192, v192, v82
	v_pk_mul_f32 v[128:129], v[128:129], v[82:83] op_sel_hi:[1,0]
	v_pk_mul_f32 v[126:127], v[126:127], v[82:83] op_sel_hi:[1,0]
	v_pk_mul_f32 v[124:125], v[124:125], v[82:83] op_sel_hi:[1,0]
	v_pk_mul_f32 v[122:123], v[122:123], v[82:83] op_sel_hi:[1,0]
	v_pk_mul_f32 v[120:121], v[120:121], v[82:83] op_sel_hi:[1,0]
	v_pk_mul_f32 v[118:119], v[118:119], v[82:83] op_sel_hi:[1,0]
	v_pk_mul_f32 v[116:117], v[116:117], v[82:83] op_sel_hi:[1,0]
	v_pk_mul_f32 v[114:115], v[114:115], v[82:83] op_sel_hi:[1,0]
	v_pk_mul_f32 v[112:113], v[112:113], v[82:83] op_sel_hi:[1,0]
	v_pk_mul_f32 v[110:111], v[110:111], v[82:83] op_sel_hi:[1,0]
	v_pk_mul_f32 v[108:109], v[108:109], v[82:83] op_sel_hi:[1,0]
	v_pk_mul_f32 v[106:107], v[106:107], v[82:83] op_sel_hi:[1,0]
	v_pk_mul_f32 v[104:105], v[104:105], v[82:83] op_sel_hi:[1,0]
	v_pk_mul_f32 v[102:103], v[102:103], v[82:83] op_sel_hi:[1,0]
	v_pk_mul_f32 v[100:101], v[100:101], v[82:83] op_sel_hi:[1,0]
	v_pk_mul_f32 v[98:99], v[98:99], v[82:83] op_sel_hi:[1,0]
.LBB0_1033:
	s_mov_b64 s[8:9], -1
	s_and_b64 vcc, exec, s[10:11]
	v_xor_b32_e32 v194, 0x80000000, v190
	s_barrier
	s_cbranch_vccz .LBB0_1035
	v_add_f32 v82, v34, v194
	v_add_f32 v83, v50, v194
	v_add_f32 v85, v35, v194
	v_add_f32 v86, v51, v194
	v_add_f32 v87, v36, v194
	v_add_f32 v88, v52, v194
	s_nop 0
	v_exp_f32_e32 v82, v82
	v_exp_f32_e32 v83, v83
	v_exp_f32_e32 v85, v85
	v_exp_f32_e32 v86, v86
	v_add_f32_e32 v84, 0, v82
	v_exp_f32_e32 v87, v87
	v_add_f32_e32 v84, v83, v84
	v_exp_f32_e32 v88, v88
	v_add_f32 v89, v37, v194
	v_add_f32_e32 v84, v84, v85
	v_exp_f32_e32 v89, v89
	v_add_f32 v90, v53, v194
	v_add_f32_e32 v84, v86, v84
	v_exp_f32_e32 v90, v90
	v_add_f32 v91, v38, v194
	v_add_f32_e32 v84, v84, v87
	v_exp_f32_e32 v91, v91
	v_add_f32 v92, v54, v194
	v_add_f32_e32 v84, v88, v84
	v_exp_f32_e32 v92, v92
	v_add_f32 v93, v39, v194
	v_add_f32_e32 v84, v84, v89
	v_exp_f32_e32 v93, v93
	v_add_f32 v94, v55, v194
	v_add_f32_e32 v84, v90, v84
	v_exp_f32_e32 v94, v94
	v_add_f32 v95, v40, v194
	v_add_f32_e32 v84, v84, v91
	v_exp_f32_e32 v95, v95
	v_add_f32 v96, v56, v194
	v_add_f32_e32 v84, v92, v84
	v_exp_f32_e32 v96, v96
	v_add_f32 v97, v41, v194
	v_add_f32_e32 v84, v84, v93
	v_exp_f32_e32 v97, v97
	v_add_f32 v66, v57, v194
	v_add_f32_e32 v84, v94, v84
	v_exp_f32_e32 v66, v66
	v_add_f32 v67, v42, v194
	v_add_f32_e32 v84, v84, v95
	v_exp_f32_e32 v67, v67
	v_add_f32 v68, v58, v194
	v_add_f32_e32 v84, v96, v84
	v_exp_f32_e32 v68, v68
	v_add_f32 v69, v43, v194
	v_add_f32_e32 v84, v84, v97
	v_exp_f32_e32 v69, v69
	v_add_f32 v70, v59, v194
	v_add_f32_e32 v84, v66, v84
	v_exp_f32_e32 v70, v70
	v_add_f32 v71, v44, v194
	v_add_f32_e32 v84, v84, v67
	v_exp_f32_e32 v71, v71
	v_add_f32 v72, v60, v194
	v_add_f32_e32 v84, v68, v84
	v_exp_f32_e32 v72, v72
	v_add_f32 v73, v45, v194
	v_add_f32_e32 v84, v84, v69
	v_exp_f32_e32 v73, v73
	v_add_f32 v74, v61, v194
	v_add_f32_e32 v84, v70, v84
	v_exp_f32_e32 v74, v74
	v_add_f32 v75, v46, v194
	v_add_f32_e32 v84, v84, v71
	v_exp_f32_e32 v75, v75
	v_add_f32 v76, v62, v194
	v_add_f32_e32 v84, v72, v84
	v_exp_f32_e32 v76, v76
	v_add_f32 v77, v47, v194
	v_add_f32_e32 v84, v84, v73
	v_exp_f32_e32 v77, v77
	v_add_f32 v78, v63, v194
	v_add_f32_e32 v84, v74, v84
	v_exp_f32_e32 v78, v78
	v_add_f32 v79, v48, v194
	v_add_f32_e32 v84, v84, v75
	v_exp_f32_e32 v79, v79
	v_add_f32 v80, v64, v194
	v_add_f32_e32 v84, v76, v84
	v_exp_f32_e32 v80, v80
	v_add_f32 v81, v49, v194
	v_add_f32_e32 v84, v84, v77
	v_exp_f32_e32 v81, v81
	v_add_f32_e32 v84, v78, v84
	v_add_f32 v195, v65, v194
	v_add_f32_e32 v84, v84, v79
	v_exp_f32_e32 v204, v195
	v_add_f32_e32 v84, v80, v84
	v_add_f32_e32 v84, v84, v81
	v_cvt_pk_bf16_f32 v196, v82, v85
	v_add_f32_e32 v195, v204, v84
	v_cvt_pk_bf16_f32 v197, v87, v89
	v_cvt_pk_bf16_f32 v198, v91, v93
	v_cvt_pk_bf16_f32 v199, v95, v97
	v_cvt_pk_bf16_f32 v200, v67, v69
	v_cvt_pk_bf16_f32 v201, v71, v73
	v_cvt_pk_bf16_f32 v202, v75, v77
	v_cvt_pk_bf16_f32 v203, v79, v81
	v_cvt_pk_bf16_f32 v214, v83, v86
	v_cvt_pk_bf16_f32 v215, v88, v90
	v_cvt_pk_bf16_f32 v216, v92, v94
	v_cvt_pk_bf16_f32 v217, v96, v66
	v_cvt_pk_bf16_f32 v218, v68, v70
	v_cvt_pk_bf16_f32 v219, v72, v74
	v_cvt_pk_bf16_f32 v220, v76, v78
	v_cvt_pk_bf16_f32 v221, v80, v204
	ds_read_b64_tr_b16 v[82:83], v193 offset:34816
	ds_read_b64_tr_b16 v[84:85], v193 offset:35328
	ds_read_b64_tr_b16 v[222:223], v193 offset:38912
	ds_read_b64_tr_b16 v[224:225], v193 offset:39424
	s_waitcnt lgkmcnt(2)
	v_mfma_f32_32x32x16_bf16 v[114:129], v[82:85], v[196:199], v[114:129]
	s_mov_b64 s[8:9], 0
	s_waitcnt lgkmcnt(0)
	v_mfma_f32_32x32x16_bf16 v[98:113], v[222:225], v[196:199], v[98:113]
	ds_read_b64_tr_b16 v[196:197], v193 offset:35840
	ds_read_b64_tr_b16 v[198:199], v193 offset:36352
	ds_read_b64_tr_b16 v[222:223], v193 offset:39936
	ds_read_b64_tr_b16 v[224:225], v193 offset:40448
	s_waitcnt lgkmcnt(2)
	v_mfma_f32_32x32x16_bf16 v[114:129], v[196:199], v[200:203], v[114:129]
	s_waitcnt lgkmcnt(0)
	v_mfma_f32_32x32x16_bf16 v[98:113], v[222:225], v[200:203], v[98:113]
	ds_read_b64_tr_b16 v[196:197], v193 offset:36864
	ds_read_b64_tr_b16 v[198:199], v193 offset:37376
	ds_read_b64_tr_b16 v[200:201], v193 offset:40960
	ds_read_b64_tr_b16 v[202:203], v193 offset:41472
	s_waitcnt lgkmcnt(2)
	v_mfma_f32_32x32x16_bf16 v[114:129], v[196:199], v[214:217], v[114:129]
	s_waitcnt lgkmcnt(0)
	v_mfma_f32_32x32x16_bf16 v[98:113], v[200:203], v[214:217], v[98:113]
	ds_read_b64_tr_b16 v[196:197], v193 offset:37888
	ds_read_b64_tr_b16 v[198:199], v193 offset:38400
	ds_read_b64_tr_b16 v[200:201], v193 offset:41984
	ds_read_b64_tr_b16 v[202:203], v193 offset:42496
	s_waitcnt lgkmcnt(2)
	v_mfma_f32_32x32x16_bf16 v[114:129], v[196:199], v[218:221], v[114:129]
	s_waitcnt lgkmcnt(0)
	v_mfma_f32_32x32x16_bf16 v[98:113], v[200:203], v[218:221], v[98:113]
; #define LAS __attribute__((address_space(3)))
; __device__ __forceinline__ void att_qk_exp(const LAS char* kb, const bf16x8 (&qf)[6], float nm, fa::f32x16& n0, fa::f32x16& n1, fa::f32x16& p0, fa::f32x16& p1, float& lsum, bf16x8 (&pf)[4]) {
;     const fa::f32x16 zero = {0.f, 0.f, 0.f, 0.f, 0.f, 0.f, 0.f, 0.f, 0.f, 0.f, 0.f, 0.f, 0.f, 0.f, 0.f, 0.f};
;     bf16x8 kc0 = *(const LAS bf16x8*)kb, kc1 = *(const LAS bf16x8*)(kb + 32 * fa::KP_A);
;     float ps = 0.f, ps2 = 0.f;
; #pragma unroll
;     for (int st = 0; st < 6; ++st) {
;         bf16x8 kn0 = kc0, kn1 = kc1;
;         if (st < 5) { kn0 = *(const LAS bf16x8*)(kb + 32 * (st + 1)); kn1 = *(const LAS bf16x8*)(kb + 32 * fa::KP_A + 32 * (st + 1)); }
;         n0 = __builtin_amdgcn_mfma_f32_32x32x16_bf16(kc0, qf[st], st == 0 ? zero : n0, 0, 0, 0);
;         n1 = __builtin_amdgcn_mfma_f32_32x32x16_bf16(kc1, qf[st], st == 0 ? zero : n1, 0, 0, 0);
;         constexpr int lo[7] = {0, 2, 6, 8, 10, 14, 16};
; #pragma unroll
;         for (int r = lo[st]; r < lo[st + 1]; ++r) {
;             p0[r] = __builtin_amdgcn_exp2f(vadd1(p0[r], nm)); p1[r] = __builtin_amdgcn_exp2f(vadd1(p1[r], nm));
;             ps += p0[r]; ps += p1[r]; }
;         kc0 = kn0; kc1 = kn1;
;         __builtin_amdgcn_sched_barrier(0);
;     }
;     lsum += ps + ps2;
;     pf[0] = fa::pack_p(p0, 0); pf[1] = fa::pack_p(p0, 8); pf[2] = fa::pack_p(p1, 0); pf[3] = fa::pack_p(p1, 8);
; }
; __device__ __forceinline__ void att_exp_pack(fa::f32x16& p0, fa::f32x16& p1, float nm, float& lsum, bf16x8 (&pf)[4]) {
;     float ps = 0.f, ps2 = 0.f;
; #pragma unroll
;     for (int r = 0; r < 16; ++r) { p0[r] = __builtin_amdgcn_exp2f(vadd1(p0[r], nm)); p1[r] = __builtin_amdgcn_exp2f(vadd1(p1[r], nm)); ps += p0[r]; ps += p1[r]; }
;     lsum += ps + ps2;
;     pf[0] = fa::pack_p(p0, 0); pf[1] = fa::pack_p(p0, 8); pf[2] = fa::pack_p(p1, 0); pf[3] = fa::pack_p(p1, 8);
; }
; __device__ __forceinline__ float att_pv_max(fa::f32x16& o0, fa::f32x16& o1, const LAS char* vb, const bf16x8 (&pf)[4], const fa::f32x16& n0, const fa::f32x16& n1) {
;     using namespace fa;
;     float ta = n0[0], tb = n1[0];
;     s16x4 a0 = vtr(vb), a1 = vtr(vb + 512), b0 = vtr(vb + 4096), b1 = vtr(vb + 4096 + 512);
; #pragma unroll
;     for (int ks = 0; ks < 4; ++ks) {
;         s16x4 na0 = a0, na1 = a1, nb0 = b0, nb1 = b1;
.LBB0_1035:
	s_andn2_b64 vcc, exec, s[8:9]
	s_cbranch_vccnz .LBB0_1037
	s_nop 7
	v_add_u32_e32 v66, s18, v188
	ds_read_b128 v[2:5], v66
	ds_read_b128 v[18:21], v66 offset:6656
	ds_read_b128 v[82:85], v66 offset:32
	v_add_f32 v22, v34, v194
	v_add_f32 v23, v50, v194
	v_add_f32 v24, v35, v194
	ds_read_b128 v[86:89], v66 offset:6688
	v_exp_f32_e32 v67, v22
	v_add_f32 v22, v51, v194
	v_exp_f32_e32 v68, v23
	s_waitcnt lgkmcnt(3)
	v_mfma_f32_32x32x16_bf16 v[2:17], v[2:5], v[132:135], 0
	v_exp_f32_e32 v69, v24
	v_exp_f32_e32 v70, v22
	s_waitcnt lgkmcnt(2)
	v_mfma_f32_32x32x16_bf16 v[18:33], v[18:21], v[132:135], 0
	v_add_f32 v34, v36, v194
	s_waitcnt lgkmcnt(1)
	v_mfma_f32_32x32x16_bf16 v[2:17], v[82:85], v[136:139], v[2:17]
	v_exp_f32_e32 v71, v34
	v_add_f32 v34, v52, v194
	ds_read_b128 v[90:93], v66 offset:64
	ds_read_b128 v[94:97], v66 offset:6720
	v_exp_f32_e32 v72, v34
	v_add_f32 v34, v37, v194
	s_nop 0
	v_exp_f32_e32 v82, v34
	v_add_f32 v34, v53, v194
	s_waitcnt lgkmcnt(2)
	v_mfma_f32_32x32x16_bf16 v[18:33], v[86:89], v[136:139], v[18:33]
	v_exp_f32_e32 v83, v34
	v_add_f32 v34, v38, v194
	s_nop 0
	v_exp_f32_e32 v84, v34
	v_add_f32 v34, v54, v194
	s_nop 0
	v_exp_f32_e32 v85, v34
	v_add_f32 v34, v39, v194
	s_nop 0
	v_exp_f32_e32 v73, v34
	v_add_f32 v34, v55, v194
	s_nop 0
	v_exp_f32_e32 v74, v34
	s_waitcnt lgkmcnt(1)
	v_mfma_f32_32x32x16_bf16 v[2:17], v[90:93], v[140:143], v[2:17]
	v_add_f32 v38, v40, v194
	ds_read_b128 v[34:37], v66 offset:96
	ds_read_b128 v[50:53], v66 offset:6752
	v_exp_f32_e32 v86, v38
	v_add_f32 v38, v56, v194
	s_nop 0
	v_exp_f32_e32 v87, v38
	v_add_f32 v38, v41, v194
	s_waitcnt lgkmcnt(2)
	v_mfma_f32_32x32x16_bf16 v[18:33], v[94:97], v[140:143], v[18:33]
	v_exp_f32_e32 v88, v38
	v_add_f32 v38, v57, v194
	s_nop 0
	v_exp_f32_e32 v89, v38
	s_waitcnt lgkmcnt(1)
	v_mfma_f32_32x32x16_bf16 v[2:17], v[34:37], v[144:147], v[2:17]
	ds_read_b128 v[38:41], v66 offset:128
	ds_read_b128 v[54:57], v66 offset:6784
	v_add_f32 v34, v42, v194
	s_nop 0
	v_exp_f32_e32 v42, v34
	v_add_f32 v34, v58, v194
	s_nop 0
	v_exp_f32_e32 v58, v34
	s_waitcnt lgkmcnt(2)
	v_mfma_f32_32x32x16_bf16 v[18:33], v[50:53], v[144:147], v[18:33]
	v_add_f32 v34, v43, v194
	s_nop 0
	v_exp_f32_e32 v43, v34
	v_add_f32 v34, v59, v194
	s_nop 0
	v_exp_f32_e32 v59, v34
	s_waitcnt lgkmcnt(1)
	v_mfma_f32_32x32x16_bf16 v[2:17], v[38:41], v[148:151], v[2:17]
	ds_read_b128 v[34:37], v66 offset:160
	ds_read_b128 v[50:53], v66 offset:6816
	v_add_f32 v38, v45, v194
	v_add_f32 v44, v44, v194
	v_add_f32 v60, v60, v194
	s_nop 0
	v_exp_f32_e32 v39, v38
	v_add_f32 v38, v61, v194
	s_waitcnt lgkmcnt(2)
	v_mfma_f32_32x32x16_bf16 v[18:33], v[54:57], v[148:151], v[18:33]
	v_exp_f32_e32 v61, v38
	v_add_f32 v38, v46, v194
	v_exp_f32_e32 v44, v44
	v_exp_f32_e32 v40, v38
	v_add_f32 v38, v62, v194
	v_exp_f32_e32 v60, v60
	v_exp_f32_e32 v62, v38
	v_add_f32 v38, v47, v194
	s_nop 0
	v_exp_f32_e32 v41, v38
	v_add_f32 v38, v63, v194
	s_nop 0
	v_exp_f32_e32 v63, v38
	v_add_f32 v38, v48, v194
	s_waitcnt lgkmcnt(1)
	v_mfma_f32_32x32x16_bf16 v[2:17], v[34:37], v[152:155], v[2:17]
	v_exp_f32_e32 v45, v38
	v_add_f32 v38, v64, v194
	v_add_f32 v34, v65, v194
	s_nop 0
	v_exp_f32_e32 v54, v38
	v_add_f32 v38, v49, v194
	v_exp_f32_e32 v49, v34
	v_add_f32_e32 v34, 0, v67
	v_add_f32_e32 v34, v68, v34
	v_add_f32_e32 v34, v34, v69
	v_add_f32_e32 v34, v70, v34
	v_add_f32_e32 v34, v34, v71
	v_add_f32_e32 v34, v72, v34
	v_add_f32_e32 v34, v34, v82
	v_add_f32_e32 v34, v83, v34
	v_add_f32_e32 v34, v34, v84
	v_add_f32_e32 v34, v85, v34
	v_add_f32_e32 v34, v34, v73
	v_add_f32_e32 v34, v74, v34
	v_add_f32_e32 v34, v34, v86
	v_add_f32_e32 v34, v87, v34
	v_add_f32_e32 v34, v34, v88
	v_add_f32_e32 v34, v89, v34
	v_add_f32_e32 v34, v34, v42
	v_add_f32_e32 v34, v58, v34
	v_add_f32_e32 v34, v34, v43
	v_add_f32_e32 v34, v59, v34
	v_add_f32_e32 v34, v34, v44
	v_add_f32_e32 v34, v60, v34
	v_add_f32_e32 v34, v34, v39
	v_add_f32_e32 v34, v61, v34
	s_waitcnt lgkmcnt(0)
	v_mfma_f32_32x32x16_bf16 v[18:33], v[50:53], v[152:155], v[18:33]
	v_add_f32_e32 v34, v34, v40
	v_add_f32_e32 v34, v62, v34
	v_exp_f32_e32 v46, v38
	v_add_f32_e32 v34, v34, v41
	v_add_f32_e32 v34, v63, v34
	v_add_f32_e32 v34, v34, v45
	v_add_f32_e32 v34, v54, v34
	v_add_f32_e32 v34, v34, v46
	v_add_f32_e32 v195, v49, v34
	v_cvt_pk_bf16_f32 v34, v67, v69
	v_cvt_pk_bf16_f32 v35, v71, v82
	v_cvt_pk_bf16_f32 v36, v84, v73
	v_cvt_pk_bf16_f32 v37, v86, v88
	v_cvt_pk_bf16_f32 v38, v42, v43
	v_cvt_pk_bf16_f32 v39, v44, v39
	v_cvt_pk_bf16_f32 v40, v40, v41
	v_cvt_pk_bf16_f32 v41, v45, v46
	v_cvt_pk_bf16_f32 v42, v68, v70
	v_cvt_pk_bf16_f32 v43, v72, v83
	v_cvt_pk_bf16_f32 v44, v85, v74
	v_cvt_pk_bf16_f32 v45, v87, v89
	v_cvt_pk_bf16_f32 v46, v58, v59
	v_cvt_pk_bf16_f32 v47, v60, v61
	v_cvt_pk_bf16_f32 v48, v62, v63
	v_cvt_pk_bf16_f32 v49, v54, v49
	ds_read_b64_tr_b16 v[50:51], v193 offset:34816
	ds_read_b64_tr_b16 v[52:53], v193 offset:35328
	ds_read_b64_tr_b16 v[54:55], v193 offset:35840
	ds_read_b64_tr_b16 v[56:57], v193 offset:36352
	s_waitcnt lgkmcnt(2)
	v_mfma_f32_32x32x16_bf16 v[114:129], v[50:53], v[34:37], v[114:129]
	ds_read_b64_tr_b16 v[50:51], v193 offset:38912
	ds_read_b64_tr_b16 v[52:53], v193 offset:39424
	ds_read_b64_tr_b16 v[58:59], v193 offset:39936
	ds_read_b64_tr_b16 v[60:61], v193 offset:40448
	s_waitcnt lgkmcnt(2)
	v_mfma_f32_32x32x16_bf16 v[98:113], v[50:53], v[34:37], v[98:113]
	ds_read_b64_tr_b16 v[34:35], v193 offset:36864
	ds_read_b64_tr_b16 v[36:37], v193 offset:37376
	ds_read_b64_tr_b16 v[50:51], v193 offset:40960
	ds_read_b64_tr_b16 v[52:53], v193 offset:41472
	v_mfma_f32_32x32x16_bf16 v[114:129], v[54:57], v[38:41], v[114:129]
	s_waitcnt lgkmcnt(4)
	v_mfma_f32_32x32x16_bf16 v[98:113], v[58:61], v[38:41], v[98:113]
	s_waitcnt lgkmcnt(2)
	v_mfma_f32_32x32x16_bf16 v[114:129], v[34:37], v[42:45], v[114:129]
	ds_read_b64_tr_b16 v[34:35], v193 offset:37888
	ds_read_b64_tr_b16 v[36:37], v193 offset:38400
	ds_read_b64_tr_b16 v[38:39], v193 offset:41984
	ds_read_b64_tr_b16 v[40:41], v193 offset:42496
	s_waitcnt lgkmcnt(4)
	v_mfma_f32_32x32x16_bf16 v[98:113], v[50:53], v[42:45], v[98:113]
	v_max_f32_e32 v42, v19, v19
	v_max_f32_e32 v43, v18, v18
	v_max_f32_e32 v42, v43, v42
	v_max3_f32 v42, v42, v20, v21
	s_waitcnt lgkmcnt(2)
	v_mfma_f32_32x32x16_bf16 v[114:129], v[34:37], v[46:49], v[114:129]
	v_max3_f32 v35, v2, v3, v4
	v_max3_f32 v42, v42, v22, v23
	v_max3_f32 v35, v35, v5, v6
	v_max3_f32 v42, v42, v24, v25
	v_max3_f32 v35, v35, v7, v8
	v_max3_f32 v34, v42, v26, v27
	v_max3_f32 v35, v35, v9, v10
	v_max3_f32 v34, v34, v28, v29
	v_max3_f32 v35, v35, v11, v12
	v_max3_f32 v35, v35, v13, v14
	v_max3_f32 v34, v34, v30, v31
	s_waitcnt lgkmcnt(0)
	v_mfma_f32_32x32x16_bf16 v[98:113], v[38:41], v[46:49], v[98:113]
	v_max3_f32 v35, v35, v15, v16
	v_max3_f32 v34, v34, v32, v33
	v_max3_f32 v191, v35, v17, v34

; #define LAS __attribute__((address_space(3)))
; __device__ __forceinline__ void att_qk_exp(const LAS char* kb, const bf16x8 (&qf)[6], float nm, fa::f32x16& n0, fa::f32x16& n1, fa::f32x16& p0, fa::f32x16& p1, float& lsum, bf16x8 (&pf)[4]) {
;     const fa::f32x16 zero = {0.f, 0.f, 0.f, 0.f, 0.f, 0.f, 0.f, 0.f, 0.f, 0.f, 0.f, 0.f, 0.f, 0.f, 0.f, 0.f};
;     bf16x8 kc0 = *(const LAS bf16x8*)kb, kc1 = *(const LAS bf16x8*)(kb + 32 * fa::KP_A);
;     float ps = 0.f, ps2 = 0.f;
; #pragma unroll
;     for (int st = 0; st < 6; ++st) {
;         bf16x8 kn0 = kc0, kn1 = kc1;
;         if (st < 5) { kn0 = *(const LAS bf16x8*)(kb + 32 * (st + 1)); kn1 = *(const LAS bf16x8*)(kb + 32 * fa::KP_A + 32 * (st + 1)); }
;         n0 = __builtin_amdgcn_mfma_f32_32x32x16_bf16(kc0, qf[st], st == 0 ? zero : n0, 0, 0, 0);
;         n1 = __builtin_amdgcn_mfma_f32_32x32x16_bf16(kc1, qf[st], st == 0 ? zero : n1, 0, 0, 0);
;         constexpr int lo[7] = {0, 2, 6, 8, 10, 14, 16};
; #pragma unroll
;         for (int r = lo[st]; r < lo[st + 1]; ++r) {
;             p0[r] = __builtin_amdgcn_exp2f(vadd1(p0[r], nm)); p1[r] = __builtin_amdgcn_exp2f(vadd1(p1[r], nm));
;             ps += p0[r]; ps += p1[r]; }
;         kc0 = kn0; kc1 = kn1;
;         __builtin_amdgcn_sched_barrier(0);
;     }
;     lsum += ps + ps2;
;     pf[0] = fa::pack_p(p0, 0); pf[1] = fa::pack_p(p0, 8); pf[2] = fa::pack_p(p1, 0); pf[3] = fa::pack_p(p1, 8);
; }
; __device__ __forceinline__ void att_exp_pack(fa::f32x16& p0, fa::f32x16& p1, float nm, float& lsum, bf16x8 (&pf)[4]) {
;     float ps = 0.f, ps2 = 0.f;
; #pragma unroll
;     for (int r = 0; r < 16; ++r) { p0[r] = __builtin_amdgcn_exp2f(vadd1(p0[r], nm)); p1[r] = __builtin_amdgcn_exp2f(vadd1(p1[r], nm)); ps += p0[r]; ps += p1[r]; }
;     lsum += ps + ps2;
;     pf[0] = fa::pack_p(p0, 0); pf[1] = fa::pack_p(p0, 8); pf[2] = fa::pack_p(p1, 0); pf[3] = fa::pack_p(p1, 8);
; }
; __device__ __forceinline__ float att_pv_max(fa::f32x16& o0, fa::f32x16& o1, const LAS char* vb, const bf16x8 (&pf)[4], const fa::f32x16& n0, const fa::f32x16& n1) {
;     using namespace fa;
;     float ta = n0[0], tb = n1[0];
;     s16x4 a0 = vtr(vb), a1 = vtr(vb + 512), b0 = vtr(vb + 4096), b1 = vtr(vb + 4096 + 512);
; #pragma unroll
;     for (int ks = 0; ks < 4; ++ks) {
;         s16x4 na0 = a0, na1 = a1, nb0 = b0, nb1 = b1;
.LBB0_2991:
	s_add_i32 s8, s8, 0
	v_add3_u32 v99, s8, v217, v188
	ds_read_b128 v[34:37], v99 offset:21504
	ds_read_b128 v[50:53], v99 offset:28160
	ds_read_b128 v[100:103], v99 offset:21536
	v_xor_b32_e32 v116, 0x80000000, v131
	v_add_f32 v2, v2, v116
	s_waitcnt lgkmcnt(1)
	v_mfma_f32_32x32x16_bf16 v[50:65], v[50:53], v[134:137], 0
	v_add_f32 v18, v18, v116
	ds_read_b128 v[104:107], v99 offset:28192
	v_add_f32 v3, v3, v116
	v_add_f32 v19, v19, v116
	v_exp_f32_e32 v2, v2
	v_exp_f32_e32 v18, v18
	v_exp_f32_e32 v3, v3
	v_mfma_f32_32x32x16_bf16 v[34:49], v[34:37], v[134:137], 0
	v_exp_f32_e32 v19, v19
	s_waitcnt lgkmcnt(1)
	v_mfma_f32_32x32x16_bf16 v[34:49], v[100:103], v[138:141], v[34:49]
	ds_read_b128 v[108:111], v99 offset:21568
	ds_read_b128 v[112:115], v99 offset:28224
	v_add_f32 v4, v4, v116
	v_add_f32 v20, v20, v116
	v_add_f32 v5, v5, v116
	v_add_f32 v21, v21, v116
	v_add_f32 v6, v6, v116
	v_add_f32 v22, v22, v116
	s_waitcnt lgkmcnt(2)
	v_mfma_f32_32x32x16_bf16 v[50:65], v[104:107], v[138:141], v[50:65]
	v_add_f32 v7, v7, v116
	v_add_f32 v23, v23, v116
	v_exp_f32_e32 v4, v4
	v_exp_f32_e32 v20, v20
	v_exp_f32_e32 v5, v5
	v_exp_f32_e32 v21, v21
	v_exp_f32_e32 v6, v6
	v_exp_f32_e32 v22, v22
	v_exp_f32_e32 v7, v7
	v_exp_f32_e32 v23, v23
	s_waitcnt lgkmcnt(1)
	v_mfma_f32_32x32x16_bf16 v[34:49], v[108:111], v[142:145], v[34:49]
	ds_read_b128 v[100:103], v99 offset:21600
	ds_read_b128 v[104:107], v99 offset:28256
	v_add_f32 v8, v8, v116
	v_add_f32 v24, v24, v116
	v_add_f32 v9, v9, v116
	v_add_f32 v25, v25, v116
	s_nop 0
	v_exp_f32_e32 v8, v8
	s_waitcnt lgkmcnt(2)
	v_mfma_f32_32x32x16_bf16 v[50:65], v[112:115], v[142:145], v[50:65]
	v_exp_f32_e32 v24, v24
	v_exp_f32_e32 v9, v9
	v_exp_f32_e32 v25, v25
	s_waitcnt lgkmcnt(1)
	v_mfma_f32_32x32x16_bf16 v[34:49], v[100:103], v[146:149], v[34:49]
	ds_read_b128 v[108:111], v99 offset:21632
	ds_read_b128 v[112:115], v99 offset:28288
	v_add_f32 v10, v10, v116
	v_add_f32 v26, v26, v116
	v_add_f32 v11, v11, v116
	v_add_f32 v27, v27, v116
	s_nop 0
	v_exp_f32_e32 v10, v10
	s_waitcnt lgkmcnt(2)
	v_mfma_f32_32x32x16_bf16 v[50:65], v[104:107], v[146:149], v[50:65]
	v_exp_f32_e32 v26, v26
	v_exp_f32_e32 v11, v11
	v_exp_f32_e32 v27, v27
	s_waitcnt lgkmcnt(1)
	v_mfma_f32_32x32x16_bf16 v[34:49], v[108:111], v[150:153], v[34:49]
	ds_read_b128 v[100:103], v99 offset:21664
	ds_read_b128 v[104:107], v99 offset:28320
	v_add_f32 v12, v12, v116
	v_add_f32 v28, v28, v116
	v_add_f32 v13, v13, v116
	v_add_f32 v29, v29, v116
	v_add_f32 v14, v14, v116
	v_add_f32 v30, v30, v116
	s_waitcnt lgkmcnt(2)
	v_mfma_f32_32x32x16_bf16 v[50:65], v[112:115], v[150:153], v[50:65]
	v_add_f32 v15, v15, v116
	v_add_f32 v31, v31, v116
	v_exp_f32_e32 v12, v12
	v_exp_f32_e32 v28, v28
	v_exp_f32_e32 v13, v13
	v_exp_f32_e32 v29, v29
	v_exp_f32_e32 v14, v14
	v_exp_f32_e32 v30, v30
	v_exp_f32_e32 v15, v15
	v_exp_f32_e32 v31, v31
	v_add_f32_e32 v99, 0, v2
	v_add_f32_e32 v99, v18, v99
	v_add_f32_e32 v99, v99, v3
	v_add_f32_e32 v99, v19, v99
	v_add_f32_e32 v99, v99, v4
	v_add_f32_e32 v99, v20, v99
	v_add_f32_e32 v99, v99, v5
	v_add_f32_e32 v99, v21, v99
	v_add_f32_e32 v99, v99, v6
	v_add_f32_e32 v99, v22, v99
	v_add_f32_e32 v99, v99, v7
	v_add_f32_e32 v99, v23, v99
	v_add_f32_e32 v99, v99, v8
	v_add_f32_e32 v99, v24, v99
	v_add_f32_e32 v99, v99, v9
	v_add_f32_e32 v99, v25, v99
	v_add_f32_e32 v99, v99, v10
	v_add_f32_e32 v99, v26, v99
	v_add_f32_e32 v99, v99, v11
	v_add_f32_e32 v99, v27, v99
	v_add_f32_e32 v99, v99, v12
	v_add_f32_e32 v99, v28, v99
	v_add_f32_e32 v99, v99, v13
	v_add_f32 v16, v16, v116
	v_add_f32_e32 v99, v29, v99
	v_exp_f32_e32 v16, v16
	v_add_f32 v32, v32, v116
	s_waitcnt lgkmcnt(1)
	v_mfma_f32_32x32x16_bf16 v[34:49], v[100:103], v[154:157], v[34:49]
	v_add_f32_e32 v99, v99, v14
	v_exp_f32_e32 v32, v32
	v_add_f32 v17, v17, v116
	v_add_f32_e32 v99, v30, v99
	v_exp_f32_e32 v17, v17
	v_add_f32 v33, v33, v116
	v_add_f32_e32 v99, v99, v15
	s_waitcnt lgkmcnt(0)
	v_mfma_f32_32x32x16_bf16 v[50:65], v[104:107], v[154:157], v[50:65]
	v_exp_f32_e32 v33, v33
	v_add_f32_e32 v99, v31, v99
	v_add_f32_e32 v99, v99, v16
	v_add_f32_e32 v99, v32, v99
	v_add_f32_e32 v99, v99, v17
	v_add_f32_e32 v99, v33, v99
	v_add_u32_e32 v221, s8, v216
	v_cvt_pk_bf16_f32 v100, v2, v3
	v_cvt_pk_bf16_f32 v101, v4, v5
	v_cvt_pk_bf16_f32 v102, v6, v7
	v_cvt_pk_bf16_f32 v103, v8, v9
	v_cvt_pk_bf16_f32 v104, v10, v11
	v_cvt_pk_bf16_f32 v105, v12, v13
	v_cvt_pk_bf16_f32 v106, v14, v15
	v_cvt_pk_bf16_f32 v107, v16, v17
	v_cvt_pk_bf16_f32 v108, v18, v19
	v_cvt_pk_bf16_f32 v109, v20, v21
	v_cvt_pk_bf16_f32 v110, v22, v23
	v_cvt_pk_bf16_f32 v111, v24, v25
	v_cvt_pk_bf16_f32 v224, v26, v27
	v_cvt_pk_bf16_f32 v225, v28, v29
	v_cvt_pk_bf16_f32 v226, v30, v31
	v_cvt_pk_bf16_f32 v227, v32, v33
	ds_read_b64_tr_b16 v[112:113], v221 offset:13312
	ds_read_b64_tr_b16 v[114:115], v221 offset:13824
	ds_read_b64_tr_b16 v[116:117], v221 offset:14336
	ds_read_b64_tr_b16 v[118:119], v221 offset:14848
	s_waitcnt lgkmcnt(2)
	v_mfma_f32_32x32x16_bf16 v[82:97], v[112:115], v[100:103], v[82:97]
	ds_read_b64_tr_b16 v[112:113], v221 offset:17408
	ds_read_b64_tr_b16 v[114:115], v221 offset:17920
	ds_read_b64_tr_b16 v[120:121], v221 offset:18432
	ds_read_b64_tr_b16 v[122:123], v221 offset:18944
	v_add_f32_e32 v99, 0, v99
	v_add_f32_e32 v220, v98, v99
	s_waitcnt lgkmcnt(2)
	v_mfma_f32_32x32x16_bf16 v[66:81], v[112:115], v[100:103], v[66:81]
	s_waitcnt lgkmcnt(0)
	v_mfma_f32_32x32x16_bf16 v[66:81], v[120:123], v[104:107], v[66:81]
	ds_read_b64_tr_b16 v[98:99], v221 offset:15360
	ds_read_b64_tr_b16 v[100:101], v221 offset:15872
	ds_read_b64_tr_b16 v[112:113], v221 offset:19456
	ds_read_b64_tr_b16 v[114:115], v221 offset:19968
	v_mfma_f32_32x32x16_bf16 v[82:97], v[116:119], v[104:107], v[82:97]
	s_waitcnt lgkmcnt(0)
	v_mfma_f32_32x32x16_bf16 v[66:81], v[112:115], v[108:111], v[66:81]
	ds_read_b64_tr_b16 v[116:117], v221 offset:16384
	ds_read_b64_tr_b16 v[118:119], v221 offset:16896
	ds_read_b64_tr_b16 v[228:229], v221 offset:20480
	ds_read_b64_tr_b16 v[230:231], v221 offset:20992
	v_mfma_f32_32x32x16_bf16 v[82:97], v[98:101], v[108:111], v[82:97]
	v_max_f32_e32 v98, v51, v51
	v_max_f32_e32 v99, v50, v50
	v_max_f32_e32 v98, v99, v98
	v_max3_f32 v98, v98, v52, v53
	v_max3_f32 v98, v98, v54, v55
	v_max3_f32 v98, v98, v56, v57
	v_max3_f32 v114, v98, v58, v59
	v_max3_f32 v98, v114, v60, v61
	v_max3_f32 v99, v34, v35, v36
	s_waitcnt lgkmcnt(2)
	v_mfma_f32_32x32x16_bf16 v[82:97], v[116:119], v[224:227], v[82:97]
	v_max3_f32 v99, v99, v37, v38
	v_max3_f32 v99, v99, v39, v40
	s_waitcnt lgkmcnt(0)
	v_mfma_f32_32x32x16_bf16 v[66:81], v[228:231], v[224:227], v[66:81]
	v_max3_f32 v99, v99, v41, v42
	v_max3_f32 v99, v99, v43, v44
	v_max3_f32 v114, v99, v45, v46
	v_max3_f32 v115, v98, v62, v63
	v_max3_f32 v114, v114, v47, v48
	v_max3_f32 v115, v115, v64, v65
	v_max3_f32 v114, v114, v49, v115
	v_cmp_gt_f32_e32 vcc, v114, v222
	s_cbranch_vccz .LBB0_2993
; __device__ __forceinline__ bf16x8 pack_p(const f32x16& p, int base) { u32x4 w; w.x = pk2(p[base], p[base + 1]); w.y = pk2(p[base + 2], p[base + 3]); w.z = pk2(p[base + 4], p[base + 5]); w.w = pk2(p[base + 6], p[base + 7]); return __builtin_bit_cast(bf16x8, w); }
; __device__ __forceinline__ float vadd1(float a, float b) { float r; asm("v_add_f32 %0, %1, %2" : "=v"(r) : "v"(a), "v"(b)); return r; }
; __device__ __forceinline__ void att_shift(float tm, bool first, float& mrun, float& lsum, fa::f32x16& o0, fa::f32x16& o1) {
;     if (first || __any(tm > mrun + 8.f)) {
;         tm = fmaxf(tm, __shfl_xor(tm, 32));
;         const float dl = first ? 0.f : fmaxf(tm - mrun, 0.f), alpha = __builtin_amdgcn_exp2f(-dl);
;         mrun = first ? tm : mrun + dl; lsum *= alpha;
; #pragma unroll
;         for (int r = 0; r < 16; ++r) { o0[r] *= alpha; o1[r] *= alpha; }
;     }
; }
; __device__ __forceinline__ void att_exp_pack(fa::f32x16& p0, fa::f32x16& p1, float nm, float& lsum, bf16x8 (&pf)[4]) {
;     float ps = 0.f, ps2 = 0.f;
; #pragma unroll
;     for (int r = 0; r < 16; ++r) { p0[r] = __builtin_amdgcn_exp2f(vadd1(p0[r], nm)); p1[r] = __builtin_amdgcn_exp2f(vadd1(p1[r], nm)); ps += p0[r]; ps += p1[r]; }
;     lsum += ps + ps2;
;     pf[0] = fa::pack_p(p0, 0); pf[1] = fa::pack_p(p0, 8); pf[2] = fa::pack_p(p1, 0); pf[3] = fa::pack_p(p1, 8);
; }
	v_and_b32_e32 v116, 64, v1
	v_xor_b32_e32 v115, 32, v1
	v_add_u32_e32 v116, 64, v116
	v_cmp_lt_i32_e32 vcc, v115, v116
	s_nop 1
	v_cndmask_b32_e32 v115, v1, v115, vcc
	v_lshlrev_b32_e32 v115, 2, v115
	ds_bpermute_b32 v115, v115, v114
	v_max_f32_e32 v114, v114, v114
	s_waitcnt lgkmcnt(0)
	v_max_f32_e32 v115, v115, v115
	v_max_f32_e32 v114, v114, v115
	v_sub_f32_e32 v114, v114, v131
	v_max_f32_e32 v115, 0, v114
	v_exp_f32_e64 v114, -v115
	v_add_f32_e32 v131, v131, v115
	v_mul_f32_e32 v220, v220, v114
	v_pk_mul_f32 v[96:97], v[96:97], v[114:115] op_sel_hi:[1,0]
	v_pk_mul_f32 v[94:95], v[94:95], v[114:115] op_sel_hi:[1,0]
	v_pk_mul_f32 v[92:93], v[92:93], v[114:115] op_sel_hi:[1,0]
	v_pk_mul_f32 v[90:91], v[90:91], v[114:115] op_sel_hi:[1,0]
	v_pk_mul_f32 v[88:89], v[88:89], v[114:115] op_sel_hi:[1,0]
	v_pk_mul_f32 v[86:87], v[86:87], v[114:115] op_sel_hi:[1,0]
	v_pk_mul_f32 v[84:85], v[84:85], v[114:115] op_sel_hi:[1,0]
	v_pk_mul_f32 v[82:83], v[82:83], v[114:115] op_sel_hi:[1,0]
	v_pk_mul_f32 v[80:81], v[80:81], v[114:115] op_sel_hi:[1,0]
	v_pk_mul_f32 v[78:79], v[78:79], v[114:115] op_sel_hi:[1,0]
	v_pk_mul_f32 v[76:77], v[76:77], v[114:115] op_sel_hi:[1,0]
	v_pk_mul_f32 v[74:75], v[74:75], v[114:115] op_sel_hi:[1,0]
	v_pk_mul_f32 v[72:73], v[72:73], v[114:115] op_sel_hi:[1,0]
	v_pk_mul_f32 v[70:71], v[70:71], v[114:115] op_sel_hi:[1,0]
	v_pk_mul_f32 v[68:69], v[68:69], v[114:115] op_sel_hi:[1,0]
	v_pk_mul_f32 v[66:67], v[66:67], v[114:115] op_sel_hi:[1,0]
.LBB0_2993:
	s_mov_b64 s[8:9], -1
	s_and_b64 vcc, exec, s[12:13]
	v_xor_b32_e32 v222, 0x80000000, v131
	s_barrier
	s_cbranch_vccz .LBB0_2995
	v_add_f32 v114, v34, v222
	v_add_f32 v115, v50, v222
	v_add_f32 v117, v35, v222
	v_add_f32 v118, v51, v222
	v_add_f32 v119, v36, v222
	v_add_f32 v120, v52, v222
	s_nop 0
	v_exp_f32_e32 v114, v114
	v_exp_f32_e32 v115, v115
	v_exp_f32_e32 v117, v117
	v_exp_f32_e32 v118, v118
	v_add_f32_e32 v116, 0, v114
	v_exp_f32_e32 v119, v119
	v_add_f32_e32 v116, v115, v116
	v_exp_f32_e32 v120, v120
	v_add_f32 v121, v37, v222
	v_add_f32_e32 v116, v116, v117
	v_exp_f32_e32 v121, v121
	v_add_f32 v122, v53, v222
	v_add_f32_e32 v116, v118, v116
	v_exp_f32_e32 v122, v122
	v_add_f32 v123, v38, v222
	v_add_f32_e32 v116, v116, v119
	v_exp_f32_e32 v123, v123
	v_add_f32 v124, v54, v222
	v_add_f32_e32 v116, v120, v116
	v_exp_f32_e32 v124, v124
	v_add_f32 v125, v39, v222
	v_add_f32_e32 v116, v116, v121
	v_exp_f32_e32 v125, v125
	v_add_f32 v126, v55, v222
	v_add_f32_e32 v116, v122, v116
	v_exp_f32_e32 v126, v126
	v_add_f32 v127, v40, v222
	v_add_f32_e32 v116, v116, v123
	v_exp_f32_e32 v127, v127
	v_add_f32 v128, v56, v222
	v_add_f32_e32 v116, v124, v116
	v_exp_f32_e32 v128, v128
	v_add_f32 v129, v41, v222
	v_add_f32_e32 v116, v116, v125
	v_exp_f32_e32 v129, v129
	v_add_f32 v98, v57, v222
	v_add_f32_e32 v116, v126, v116
	v_exp_f32_e32 v98, v98
	v_add_f32 v99, v42, v222
	v_add_f32_e32 v116, v116, v127
	v_exp_f32_e32 v99, v99
	v_add_f32 v100, v58, v222
	v_add_f32_e32 v116, v128, v116
	v_exp_f32_e32 v100, v100
	v_add_f32 v101, v43, v222
	v_add_f32_e32 v116, v116, v129
	v_exp_f32_e32 v101, v101
	v_add_f32 v102, v59, v222
	v_add_f32_e32 v116, v98, v116
	v_exp_f32_e32 v102, v102
	v_add_f32 v103, v44, v222
	v_add_f32_e32 v116, v116, v99
	v_exp_f32_e32 v103, v103
	v_add_f32 v104, v60, v222
	v_add_f32_e32 v116, v100, v116
	v_exp_f32_e32 v104, v104
	v_add_f32 v105, v45, v222
	v_add_f32_e32 v116, v116, v101
	v_exp_f32_e32 v105, v105
	v_add_f32 v106, v61, v222
	v_add_f32_e32 v116, v102, v116
	v_exp_f32_e32 v106, v106
	v_add_f32 v107, v46, v222
	v_add_f32_e32 v116, v116, v103
	v_exp_f32_e32 v107, v107
	v_add_f32 v108, v62, v222
	v_add_f32_e32 v116, v104, v116
	v_exp_f32_e32 v108, v108
	v_add_f32 v109, v47, v222
	v_add_f32_e32 v116, v116, v105
	v_exp_f32_e32 v109, v109
	v_add_f32 v110, v63, v222
	v_add_f32_e32 v116, v106, v116
	v_exp_f32_e32 v110, v110
	v_add_f32 v111, v48, v222
	v_add_f32_e32 v116, v116, v107
	v_exp_f32_e32 v111, v111
	v_add_f32 v112, v64, v222
	v_add_f32_e32 v116, v108, v116
	v_exp_f32_e32 v112, v112
	v_add_f32 v113, v49, v222
	v_add_f32_e32 v116, v116, v109
	v_exp_f32_e32 v113, v113
	v_add_f32_e32 v116, v110, v116
	v_add_f32 v223, v65, v222
	v_add_f32_e32 v116, v116, v111
	v_exp_f32_e32 v239, v223
	v_add_f32_e32 v116, v112, v116
	v_add_f32_e32 v116, v116, v113
	v_cvt_pk_bf16_f32 v224, v114, v117
	v_add_f32_e32 v223, v239, v116
	v_cvt_pk_bf16_f32 v225, v119, v121
	v_cvt_pk_bf16_f32 v226, v123, v125
	v_cvt_pk_bf16_f32 v227, v127, v129
	v_cvt_pk_bf16_f32 v228, v99, v101
	v_cvt_pk_bf16_f32 v229, v103, v105
	v_cvt_pk_bf16_f32 v230, v107, v109
	v_cvt_pk_bf16_f32 v231, v111, v113
	v_cvt_pk_bf16_f32 v232, v115, v118
	v_cvt_pk_bf16_f32 v233, v120, v122
	v_cvt_pk_bf16_f32 v234, v124, v126
	v_cvt_pk_bf16_f32 v235, v128, v98
	v_cvt_pk_bf16_f32 v236, v100, v102
	v_cvt_pk_bf16_f32 v237, v104, v106
	v_cvt_pk_bf16_f32 v238, v108, v110
	v_cvt_pk_bf16_f32 v239, v112, v239
	ds_read_b64_tr_b16 v[114:115], v221 offset:34816
	ds_read_b64_tr_b16 v[116:117], v221 offset:35328
	ds_read_b64_tr_b16 v[240:241], v221 offset:38912
	ds_read_b64_tr_b16 v[242:243], v221 offset:39424
	s_waitcnt lgkmcnt(2)
	v_mfma_f32_32x32x16_bf16 v[82:97], v[114:117], v[224:227], v[82:97]
	s_mov_b64 s[8:9], 0
	s_waitcnt lgkmcnt(0)
	v_mfma_f32_32x32x16_bf16 v[66:81], v[240:243], v[224:227], v[66:81]
	ds_read_b64_tr_b16 v[224:225], v221 offset:35840
	ds_read_b64_tr_b16 v[226:227], v221 offset:36352
	ds_read_b64_tr_b16 v[240:241], v221 offset:39936
	ds_read_b64_tr_b16 v[242:243], v221 offset:40448
	s_waitcnt lgkmcnt(2)
	v_mfma_f32_32x32x16_bf16 v[82:97], v[224:227], v[228:231], v[82:97]
	s_waitcnt lgkmcnt(0)
	v_mfma_f32_32x32x16_bf16 v[66:81], v[240:243], v[228:231], v[66:81]
	ds_read_b64_tr_b16 v[224:225], v221 offset:36864
	ds_read_b64_tr_b16 v[226:227], v221 offset:37376
	ds_read_b64_tr_b16 v[228:229], v221 offset:40960
	ds_read_b64_tr_b16 v[230:231], v221 offset:41472
	s_waitcnt lgkmcnt(2)
	v_mfma_f32_32x32x16_bf16 v[82:97], v[224:227], v[232:235], v[82:97]
	s_waitcnt lgkmcnt(0)
	v_mfma_f32_32x32x16_bf16 v[66:81], v[228:231], v[232:235], v[66:81]
	ds_read_b64_tr_b16 v[224:225], v221 offset:37888
	ds_read_b64_tr_b16 v[226:227], v221 offset:38400
	ds_read_b64_tr_b16 v[228:229], v221 offset:41984
	ds_read_b64_tr_b16 v[230:231], v221 offset:42496
	s_waitcnt lgkmcnt(2)
	v_mfma_f32_32x32x16_bf16 v[82:97], v[224:227], v[236:239], v[82:97]
	s_waitcnt lgkmcnt(0)
	v_mfma_f32_32x32x16_bf16 v[66:81], v[228:231], v[236:239], v[66:81]
; #define LAS __attribute__((address_space(3)))
; __device__ __forceinline__ void att_qk_exp(const LAS char* kb, const bf16x8 (&qf)[6], float nm, fa::f32x16& n0, fa::f32x16& n1, fa::f32x16& p0, fa::f32x16& p1, float& lsum, bf16x8 (&pf)[4]) {
;     const fa::f32x16 zero = {0.f, 0.f, 0.f, 0.f, 0.f, 0.f, 0.f, 0.f, 0.f, 0.f, 0.f, 0.f, 0.f, 0.f, 0.f, 0.f};
;     bf16x8 kc0 = *(const LAS bf16x8*)kb, kc1 = *(const LAS bf16x8*)(kb + 32 * fa::KP_A);
;     float ps = 0.f, ps2 = 0.f;
; #pragma unroll
;     for (int st = 0; st < 6; ++st) {
;         bf16x8 kn0 = kc0, kn1 = kc1;
;         if (st < 5) { kn0 = *(const LAS bf16x8*)(kb + 32 * (st + 1)); kn1 = *(const LAS bf16x8*)(kb + 32 * fa::KP_A + 32 * (st + 1)); }
;         n0 = __builtin_amdgcn_mfma_f32_32x32x16_bf16(kc0, qf[st], st == 0 ? zero : n0, 0, 0, 0);
;         n1 = __builtin_amdgcn_mfma_f32_32x32x16_bf16(kc1, qf[st], st == 0 ? zero : n1, 0, 0, 0);
;         constexpr int lo[7] = {0, 2, 6, 8, 10, 14, 16};
; #pragma unroll
;         for (int r = lo[st]; r < lo[st + 1]; ++r) {
;             p0[r] = __builtin_amdgcn_exp2f(vadd1(p0[r], nm)); p1[r] = __builtin_amdgcn_exp2f(vadd1(p1[r], nm));
;             ps += p0[r]; ps += p1[r]; }
;         kc0 = kn0; kc1 = kn1;
;         __builtin_amdgcn_sched_barrier(0);
;     }
;     lsum += ps + ps2;
;     pf[0] = fa::pack_p(p0, 0); pf[1] = fa::pack_p(p0, 8); pf[2] = fa::pack_p(p1, 0); pf[3] = fa::pack_p(p1, 8);
; }
; __device__ __forceinline__ void att_exp_pack(fa::f32x16& p0, fa::f32x16& p1, float nm, float& lsum, bf16x8 (&pf)[4]) {
;     float ps = 0.f, ps2 = 0.f;
; #pragma unroll
;     for (int r = 0; r < 16; ++r) { p0[r] = __builtin_amdgcn_exp2f(vadd1(p0[r], nm)); p1[r] = __builtin_amdgcn_exp2f(vadd1(p1[r], nm)); ps += p0[r]; ps += p1[r]; }
;     lsum += ps + ps2;
;     pf[0] = fa::pack_p(p0, 0); pf[1] = fa::pack_p(p0, 8); pf[2] = fa::pack_p(p1, 0); pf[3] = fa::pack_p(p1, 8);
; }
; __device__ __forceinline__ float att_pv_max(fa::f32x16& o0, fa::f32x16& o1, const LAS char* vb, const bf16x8 (&pf)[4], const fa::f32x16& n0, const fa::f32x16& n1) {
;     using namespace fa;
;     float ta = n0[0], tb = n1[0];
;     s16x4 a0 = vtr(vb), a1 = vtr(vb + 512), b0 = vtr(vb + 4096), b1 = vtr(vb + 4096 + 512);
; #pragma unroll
;     for (int ks = 0; ks < 4; ++ks) {
;         s16x4 na0 = a0, na1 = a1, nb0 = b0, nb1 = b1;
.LBB0_2995:
	s_andn2_b64 vcc, exec, s[8:9]
	s_cbranch_vccnz .LBB0_2997
	s_nop 7
	v_add_u32_e32 v98, s19, v218
	ds_read_b128 v[2:5], v98
	ds_read_b128 v[18:21], v98 offset:6656
	ds_read_b128 v[114:117], v98 offset:32
	v_add_f32 v22, v34, v222
	v_add_f32 v23, v50, v222
	v_add_f32 v24, v35, v222
	ds_read_b128 v[118:121], v98 offset:6688
	v_exp_f32_e32 v99, v22
	v_add_f32 v22, v51, v222
	v_exp_f32_e32 v100, v23
	s_waitcnt lgkmcnt(3)
	v_mfma_f32_32x32x16_bf16 v[2:17], v[2:5], v[134:137], 0
	v_exp_f32_e32 v101, v24
	v_exp_f32_e32 v102, v22
	s_waitcnt lgkmcnt(2)
	v_mfma_f32_32x32x16_bf16 v[18:33], v[18:21], v[134:137], 0
	v_add_f32 v34, v36, v222
	s_waitcnt lgkmcnt(1)
	v_mfma_f32_32x32x16_bf16 v[2:17], v[114:117], v[138:141], v[2:17]
	v_exp_f32_e32 v103, v34
	v_add_f32 v34, v52, v222
	ds_read_b128 v[122:125], v98 offset:64
	ds_read_b128 v[126:129], v98 offset:6720
	v_exp_f32_e32 v104, v34
	v_add_f32 v34, v37, v222
	s_nop 0
	v_exp_f32_e32 v114, v34
	v_add_f32 v34, v53, v222
	s_waitcnt lgkmcnt(2)
	v_mfma_f32_32x32x16_bf16 v[18:33], v[118:121], v[138:141], v[18:33]
	v_exp_f32_e32 v115, v34
	v_add_f32 v34, v38, v222
	s_nop 0
	v_exp_f32_e32 v116, v34
	v_add_f32 v34, v54, v222
	s_nop 0
	v_exp_f32_e32 v117, v34
	v_add_f32 v34, v39, v222
	s_nop 0
	v_exp_f32_e32 v105, v34
	v_add_f32 v34, v55, v222
	s_nop 0
	v_exp_f32_e32 v106, v34
	s_waitcnt lgkmcnt(1)
	v_mfma_f32_32x32x16_bf16 v[2:17], v[122:125], v[142:145], v[2:17]
	v_add_f32 v38, v40, v222
	ds_read_b128 v[34:37], v98 offset:96
	ds_read_b128 v[50:53], v98 offset:6752
	v_exp_f32_e32 v118, v38
	v_add_f32 v38, v56, v222
	s_nop 0
	v_exp_f32_e32 v119, v38
	v_add_f32 v38, v41, v222
	s_waitcnt lgkmcnt(2)
	v_mfma_f32_32x32x16_bf16 v[18:33], v[126:129], v[142:145], v[18:33]
	v_exp_f32_e32 v120, v38
	v_add_f32 v38, v57, v222
	s_nop 0
	v_exp_f32_e32 v121, v38
	s_waitcnt lgkmcnt(1)
	v_mfma_f32_32x32x16_bf16 v[2:17], v[34:37], v[146:149], v[2:17]
	ds_read_b128 v[38:41], v98 offset:128
	ds_read_b128 v[54:57], v98 offset:6784
	v_add_f32 v34, v42, v222
	s_nop 0
	v_exp_f32_e32 v42, v34
	v_add_f32 v34, v58, v222
	s_nop 0
	v_exp_f32_e32 v58, v34
	s_waitcnt lgkmcnt(2)
	v_mfma_f32_32x32x16_bf16 v[18:33], v[50:53], v[146:149], v[18:33]
	v_add_f32 v34, v43, v222
	s_nop 0
	v_exp_f32_e32 v43, v34
	v_add_f32 v34, v59, v222
	s_nop 0
	v_exp_f32_e32 v59, v34
	s_waitcnt lgkmcnt(1)
	v_mfma_f32_32x32x16_bf16 v[2:17], v[38:41], v[150:153], v[2:17]
	ds_read_b128 v[34:37], v98 offset:160
	ds_read_b128 v[50:53], v98 offset:6816
	v_add_f32 v38, v45, v222
	v_add_f32 v44, v44, v222
	v_add_f32 v60, v60, v222
	s_nop 0
	v_exp_f32_e32 v39, v38
	v_add_f32 v38, v61, v222
	s_waitcnt lgkmcnt(2)
	v_mfma_f32_32x32x16_bf16 v[18:33], v[54:57], v[150:153], v[18:33]
	v_exp_f32_e32 v61, v38
	v_add_f32 v38, v46, v222
	v_exp_f32_e32 v44, v44
	v_exp_f32_e32 v40, v38
	v_add_f32 v38, v62, v222
	v_exp_f32_e32 v60, v60
	v_exp_f32_e32 v62, v38
	v_add_f32 v38, v47, v222
	s_nop 0
	v_exp_f32_e32 v41, v38
	v_add_f32 v38, v63, v222
	s_nop 0
	v_exp_f32_e32 v63, v38
	v_add_f32 v38, v48, v222
	s_waitcnt lgkmcnt(1)
	v_mfma_f32_32x32x16_bf16 v[2:17], v[34:37], v[154:157], v[2:17]
	v_exp_f32_e32 v45, v38
	v_add_f32 v38, v64, v222
	v_add_f32 v34, v65, v222
	s_nop 0
	v_exp_f32_e32 v54, v38
	v_add_f32 v38, v49, v222
	v_exp_f32_e32 v49, v34
	v_add_f32_e32 v34, 0, v99
	v_add_f32_e32 v34, v100, v34
	v_add_f32_e32 v34, v34, v101
	v_add_f32_e32 v34, v102, v34
	v_add_f32_e32 v34, v34, v103
	v_add_f32_e32 v34, v104, v34
	v_add_f32_e32 v34, v34, v114
	v_add_f32_e32 v34, v115, v34
	v_add_f32_e32 v34, v34, v116
	v_add_f32_e32 v34, v117, v34
	v_add_f32_e32 v34, v34, v105
	v_add_f32_e32 v34, v106, v34
	v_add_f32_e32 v34, v34, v118
	v_add_f32_e32 v34, v119, v34
	v_add_f32_e32 v34, v34, v120
	v_add_f32_e32 v34, v121, v34
	v_add_f32_e32 v34, v34, v42
	v_add_f32_e32 v34, v58, v34
	v_add_f32_e32 v34, v34, v43
	v_add_f32_e32 v34, v59, v34
	v_add_f32_e32 v34, v34, v44
	v_add_f32_e32 v34, v60, v34
	v_add_f32_e32 v34, v34, v39
	v_add_f32_e32 v34, v61, v34
	s_waitcnt lgkmcnt(0)
	v_mfma_f32_32x32x16_bf16 v[18:33], v[50:53], v[154:157], v[18:33]
	v_add_f32_e32 v34, v34, v40
	v_add_f32_e32 v34, v62, v34
	v_exp_f32_e32 v46, v38
	v_add_f32_e32 v34, v34, v41
	v_add_f32_e32 v34, v63, v34
	v_add_f32_e32 v34, v34, v45
	v_add_f32_e32 v34, v54, v34
	v_add_f32_e32 v34, v34, v46
	v_add_f32_e32 v223, v49, v34
	v_cvt_pk_bf16_f32 v34, v99, v101
	v_cvt_pk_bf16_f32 v35, v103, v114
	v_cvt_pk_bf16_f32 v36, v116, v105
	v_cvt_pk_bf16_f32 v37, v118, v120
	v_cvt_pk_bf16_f32 v38, v42, v43
	v_cvt_pk_bf16_f32 v39, v44, v39
	v_cvt_pk_bf16_f32 v40, v40, v41
	v_cvt_pk_bf16_f32 v41, v45, v46
	v_cvt_pk_bf16_f32 v42, v100, v102
	v_cvt_pk_bf16_f32 v43, v104, v115
	v_cvt_pk_bf16_f32 v44, v117, v106
	v_cvt_pk_bf16_f32 v45, v119, v121
	v_cvt_pk_bf16_f32 v46, v58, v59
	v_cvt_pk_bf16_f32 v47, v60, v61
	v_cvt_pk_bf16_f32 v48, v62, v63
	v_cvt_pk_bf16_f32 v49, v54, v49
	ds_read_b64_tr_b16 v[50:51], v221 offset:34816
	ds_read_b64_tr_b16 v[52:53], v221 offset:35328
	ds_read_b64_tr_b16 v[54:55], v221 offset:35840
	ds_read_b64_tr_b16 v[56:57], v221 offset:36352
	s_waitcnt lgkmcnt(2)
	v_mfma_f32_32x32x16_bf16 v[82:97], v[50:53], v[34:37], v[82:97]
	ds_read_b64_tr_b16 v[50:51], v221 offset:38912
	ds_read_b64_tr_b16 v[52:53], v221 offset:39424
	ds_read_b64_tr_b16 v[58:59], v221 offset:39936
	ds_read_b64_tr_b16 v[60:61], v221 offset:40448
	s_waitcnt lgkmcnt(2)
	v_mfma_f32_32x32x16_bf16 v[66:81], v[50:53], v[34:37], v[66:81]
	ds_read_b64_tr_b16 v[34:35], v221 offset:36864
	ds_read_b64_tr_b16 v[36:37], v221 offset:37376
	ds_read_b64_tr_b16 v[50:51], v221 offset:40960
	ds_read_b64_tr_b16 v[52:53], v221 offset:41472
	v_mfma_f32_32x32x16_bf16 v[82:97], v[54:57], v[38:41], v[82:97]
	s_waitcnt lgkmcnt(4)
	v_mfma_f32_32x32x16_bf16 v[66:81], v[58:61], v[38:41], v[66:81]
	s_waitcnt lgkmcnt(2)
	v_mfma_f32_32x32x16_bf16 v[82:97], v[34:37], v[42:45], v[82:97]
	ds_read_b64_tr_b16 v[34:35], v221 offset:37888
	ds_read_b64_tr_b16 v[36:37], v221 offset:38400
	ds_read_b64_tr_b16 v[38:39], v221 offset:41984
	ds_read_b64_tr_b16 v[40:41], v221 offset:42496
	s_waitcnt lgkmcnt(4)
	v_mfma_f32_32x32x16_bf16 v[66:81], v[50:53], v[42:45], v[66:81]
	v_max_f32_e32 v42, v19, v19
	v_max_f32_e32 v43, v18, v18
	v_max_f32_e32 v42, v43, v42
	v_max3_f32 v42, v42, v20, v21
	s_waitcnt lgkmcnt(2)
	v_mfma_f32_32x32x16_bf16 v[82:97], v[34:37], v[46:49], v[82:97]
	v_max3_f32 v35, v2, v3, v4
	v_max3_f32 v42, v42, v22, v23
	v_max3_f32 v35, v35, v5, v6
	v_max3_f32 v42, v42, v24, v25
	v_max3_f32 v35, v35, v7, v8
	v_max3_f32 v34, v42, v26, v27
	v_max3_f32 v35, v35, v9, v10
	v_max3_f32 v34, v34, v28, v29
	v_max3_f32 v35, v35, v11, v12
	v_max3_f32 v35, v35, v13, v14
	v_max3_f32 v34, v34, v30, v31
	s_waitcnt lgkmcnt(0)
	v_mfma_f32_32x32x16_bf16 v[66:81], v[38:41], v[46:49], v[66:81]
	v_max3_f32 v35, v35, v15, v16
	v_max3_f32 v34, v34, v32, v33
	v_max3_f32 v201, v35, v17, v34
